# v25 + up-GEMM epilogue: relu quieting fused, always-true store guards dropped (with store-data hazard pads), conditional vmcnt(24) after the epilogue (P7 only)
# baseline (speedup 1.0000x reference)
; __device__ __forceinline__ unsigned cvt_pk_bf16(float lo, float hi) { unsigned r; asm volatile("v_cvt_pk_bf16_f32 %0, %1, %2" : "=v"(r) : "v"(lo), "v"(hi)); return r; }
;     __device__ __forceinline__ void operator()(const f32x4 (&acc)[2][2][4][2], const Unit& u, int wr, int wc, int fr, int fq) const {
;     ...
;         for (int ai = 0; ai < 2; ++ai)
; #pragma unroll
;             for (int m = 0; m < 4; ++m) { bf16_t* rowp = O + (size_t)(row0 + ai * HALF + m * 16) * ldc + col0;
; #pragma unroll
;                 for (int bj = 0; bj < 2; ++bj) { f32x4 v0 = acc[ai][bj][m][0], v1 = acc[ai][bj][m][1];
;                     if (ROWSCALE) { v0 = v0 * rs[ai][m]; v1 = v1 * rs[ai][m]; }
;                     if (ACT == 2) {
; #pragma unroll
;                         for (int e = 0; e < 4; ++e) { const float a = fmaxf(v0[e], 0.f), b = fmaxf(v1[e], 0.f); v0[e] = a * a; v1[e] = b * b; } }
;                     u32x4 w; w.x = cvt_pk_bf16(v0[0], v0[1]); w.y = cvt_pk_bf16(v0[2], v0[3]); w.z = cvt_pk_bf16(v1[0], v1[1]); w.w = cvt_pk_bf16(v1[2], v1[3]);
;                     if (col0 + bj * CBS < ncols) *(u32x4*)(rowp + bj * CBS) = w; } }
.LBB0_1316:
	s_mov_b32 s101, 1
	v_lshl_add_u32 v148, s8, 8, v1
	v_ashrrev_i32_e32 v149, 31, v148
	v_max_f32_e32 v122, 0, v122
	v_max_f32_e32 v123, 0, v123
	v_max_f32_e32 v124, 0, v124
	v_lshl_or_b32 v146, s36, 8, v153
	v_lshlrev_b64 v[150:151], 13, v[148:149]
	v_mul_f32_e32 v157, v122, v122
	v_max_f32_e32 v122, v127, v127
	v_mul_f32_e32 v127, v123, v123
	v_max_f32_e32 v123, v128, v128
	v_mul_f32_e32 v128, v124, v124
	v_ashrrev_i32_e32 v147, 31, v146
	v_lshl_add_u64 v[150:151], s[52:53], 0, v[150:151]
	v_max_f32_e32 v122, 0, v122
	v_max_f32_e32 v123, 0, v123
	v_max_f32_e32 v124, 0, v129
	v_max_f32_e32 v125, 0, v125
	v_lshl_add_u64 v[150:151], v[146:147], 1, v[150:151]
	v_max_f32_e32 v126, 0, v126
	v_mul_f32_e32 v122, v122, v122
	v_mul_f32_e32 v123, v123, v123
	v_mul_f32_e32 v124, v124, v124
	v_mul_f32_e32 v125, v125, v125
	v_cmp_gt_i32_e32 vcc, 2.0, v146
	v_mul_f32_e32 v126, v126, v126
	v_cvt_pk_bf16_f32 v122, v126, v122
	v_cvt_pk_bf16_f32 v123, v123, v124
	v_cvt_pk_bf16_f32 v124, v157, v127
	v_cvt_pk_bf16_f32 v125, v128, v125
	global_store_dwordx4 v[150:151], v[122:125], off
	s_nop 0
	v_max_f32_e32 v114, 0, v114
	v_mul_f32_e32 v122, v114, v114
	v_max_f32_e32 v118, 0, v118
	v_max_f32_e32 v114, 0, v119
	v_max_f32_e32 v115, 0, v115
	v_max_f32_e32 v116, 0, v116
	v_mul_f32_e32 v118, v118, v118
	v_mul_f32_e32 v114, v114, v114
	v_mul_f32_e32 v119, v115, v115
	v_max_f32_e32 v115, v120, v120
	v_mul_f32_e32 v120, v116, v116
	v_max_f32_e32 v115, 0, v115
	v_max_f32_e32 v116, 0, v121
	v_max_f32_e32 v117, 0, v117
	v_cvt_pk_bf16_f32 v114, v118, v114
	v_or_b32_e32 v118, 32, v146
	v_mul_f32_e32 v115, v115, v115
	v_mul_f32_e32 v116, v116, v116
	v_mul_f32_e32 v117, v117, v117
	v_cmp_gt_i32_e64 s[8:9], 2.0, v118
	v_cvt_pk_bf16_f32 v115, v115, v116
	v_cvt_pk_bf16_f32 v116, v122, v119
	v_cvt_pk_bf16_f32 v117, v120, v117
	global_store_dwordx4 v[150:151], v[114:117], off offset:64
	s_nop 0
	s_nop 0
	v_or_b32_e32 v114, 16, v148
	v_ashrrev_i32_e32 v115, 31, v114
	v_max_f32_e32 v106, 0, v106
	v_max_f32_e32 v107, 0, v107
	v_max_f32_e32 v108, 0, v108
	v_lshlrev_b64 v[114:115], 13, v[114:115]
	v_mul_f32_e32 v116, v106, v106
	v_max_f32_e32 v106, v111, v111
	v_mul_f32_e32 v111, v107, v107
	v_max_f32_e32 v107, v112, v112
	v_mul_f32_e32 v112, v108, v108
	v_lshl_add_u64 v[114:115], s[52:53], 0, v[114:115]
	v_max_f32_e32 v106, 0, v106
	v_max_f32_e32 v107, 0, v107
	v_max_f32_e32 v108, 0, v113
	v_max_f32_e32 v109, 0, v109
	v_lshl_add_u64 v[114:115], v[146:147], 1, v[114:115]
	v_max_f32_e32 v110, 0, v110
	v_mul_f32_e32 v106, v106, v106
	v_mul_f32_e32 v107, v107, v107
	v_mul_f32_e32 v108, v108, v108
	v_mul_f32_e32 v109, v109, v109
	v_mul_f32_e32 v110, v110, v110
	v_cvt_pk_bf16_f32 v106, v110, v106
	v_cvt_pk_bf16_f32 v107, v107, v108
	v_cvt_pk_bf16_f32 v108, v116, v111
	v_cvt_pk_bf16_f32 v109, v112, v109
	global_store_dwordx4 v[114:115], v[106:109], off
	v_max_f32_e32 v98, 0, v98
	v_max_f32_e32 v99, 0, v99
	v_max_f32_e32 v100, 0, v100
	v_mul_f32_e32 v106, v98, v98
	v_max_f32_e32 v98, v103, v103
	v_mul_f32_e32 v103, v99, v99
	v_max_f32_e32 v99, v104, v104
	v_mul_f32_e32 v104, v100, v100
	v_max_f32_e32 v98, 0, v98
	v_max_f32_e32 v99, 0, v99
	v_max_f32_e32 v100, 0, v105
	v_max_f32_e32 v101, 0, v101
	v_max_f32_e32 v102, 0, v102
	v_mul_f32_e32 v98, v98, v98
	v_mul_f32_e32 v99, v99, v99
	v_mul_f32_e32 v100, v100, v100
	v_mul_f32_e32 v101, v101, v101
	v_mul_f32_e32 v102, v102, v102
	v_cvt_pk_bf16_f32 v98, v102, v98
	v_cvt_pk_bf16_f32 v99, v99, v100
	v_cvt_pk_bf16_f32 v100, v106, v103
	v_cvt_pk_bf16_f32 v101, v104, v101
	global_store_dwordx4 v[114:115], v[98:101], off offset:64
	s_nop 0
	s_nop 0
	v_or_b32_e32 v98, 32, v148
	v_ashrrev_i32_e32 v99, 31, v98
	v_max_f32_e32 v90, 0, v90
	v_max_f32_e32 v91, 0, v91
	v_max_f32_e32 v92, 0, v92
	v_lshlrev_b64 v[98:99], 13, v[98:99]
	v_mul_f32_e32 v100, v90, v90
	v_max_f32_e32 v90, v95, v95
	v_mul_f32_e32 v95, v91, v91
	v_max_f32_e32 v91, v96, v96
	v_mul_f32_e32 v96, v92, v92
	v_lshl_add_u64 v[98:99], s[52:53], 0, v[98:99]
	v_max_f32_e32 v90, 0, v90
	v_max_f32_e32 v91, 0, v91
	v_max_f32_e32 v92, 0, v97
	v_max_f32_e32 v93, 0, v93
	v_lshl_add_u64 v[98:99], v[146:147], 1, v[98:99]
	v_max_f32_e32 v94, 0, v94
	v_mul_f32_e32 v90, v90, v90
	v_mul_f32_e32 v91, v91, v91
	v_mul_f32_e32 v92, v92, v92
	v_mul_f32_e32 v93, v93, v93
	v_mul_f32_e32 v94, v94, v94
	v_cvt_pk_bf16_f32 v90, v94, v90
	v_cvt_pk_bf16_f32 v91, v91, v92
	v_cvt_pk_bf16_f32 v92, v100, v95
	v_cvt_pk_bf16_f32 v93, v96, v93
	global_store_dwordx4 v[98:99], v[90:93], off
	v_max_f32_e32 v82, 0, v82
	v_max_f32_e32 v83, 0, v83
	v_max_f32_e32 v84, 0, v84
	v_mul_f32_e32 v90, v82, v82
	v_max_f32_e32 v82, v87, v87
	v_mul_f32_e32 v87, v83, v83
	v_max_f32_e32 v83, v88, v88
	v_mul_f32_e32 v88, v84, v84
	v_max_f32_e32 v82, 0, v82
	v_max_f32_e32 v83, 0, v83
	v_max_f32_e32 v84, 0, v89
	v_max_f32_e32 v85, 0, v85
	v_max_f32_e32 v86, 0, v86
	v_mul_f32_e32 v82, v82, v82
	v_mul_f32_e32 v83, v83, v83
	v_mul_f32_e32 v84, v84, v84
	v_mul_f32_e32 v85, v85, v85
	v_mul_f32_e32 v86, v86, v86
	v_cvt_pk_bf16_f32 v82, v86, v82
	v_cvt_pk_bf16_f32 v83, v83, v84
	v_cvt_pk_bf16_f32 v84, v90, v87
	v_cvt_pk_bf16_f32 v85, v88, v85
	global_store_dwordx4 v[98:99], v[82:85], off offset:64
	s_nop 0
	s_nop 0
	v_or_b32_e32 v82, 48, v148
	v_ashrrev_i32_e32 v83, 31, v82
	v_max_f32_e32 v74, 0, v74
	v_max_f32_e32 v75, 0, v75
	v_max_f32_e32 v76, 0, v76
	v_lshlrev_b64 v[82:83], 13, v[82:83]
	v_mul_f32_e32 v84, v74, v74
	v_max_f32_e32 v74, v79, v79
	v_mul_f32_e32 v79, v75, v75
	v_max_f32_e32 v75, v80, v80
	v_mul_f32_e32 v80, v76, v76
	v_lshl_add_u64 v[82:83], s[52:53], 0, v[82:83]
	v_max_f32_e32 v74, 0, v74
	v_max_f32_e32 v75, 0, v75
; __device__ __forceinline__ unsigned cvt_pk_bf16(float lo, float hi) { unsigned r; asm volatile("v_cvt_pk_bf16_f32 %0, %1, %2" : "=v"(r) : "v"(lo), "v"(hi)); return r; }
;     __device__ __forceinline__ void operator()(const f32x4 (&acc)[2][2][4][2], const Unit& u, int wr, int wc, int fr, int fq) const {
;     ...
;         for (int ai = 0; ai < 2; ++ai)
; #pragma unroll
;             for (int m = 0; m < 4; ++m) { bf16_t* rowp = O + (size_t)(row0 + ai * HALF + m * 16) * ldc + col0;
; #pragma unroll
;                 for (int bj = 0; bj < 2; ++bj) { f32x4 v0 = acc[ai][bj][m][0], v1 = acc[ai][bj][m][1];
;                     if (ROWSCALE) { v0 = v0 * rs[ai][m]; v1 = v1 * rs[ai][m]; }
;                     if (ACT == 2) {
; #pragma unroll
;                         for (int e = 0; e < 4; ++e) { const float a = fmaxf(v0[e], 0.f), b = fmaxf(v1[e], 0.f); v0[e] = a * a; v1[e] = b * b; } }
;                     u32x4 w; w.x = cvt_pk_bf16(v0[0], v0[1]); w.y = cvt_pk_bf16(v0[2], v0[3]); w.z = cvt_pk_bf16(v1[0], v1[1]); w.w = cvt_pk_bf16(v1[2], v1[3]);
;                     if (col0 + bj * CBS < ncols) *(u32x4*)(rowp + bj * CBS) = w; } }
	v_max_f32_e32 v76, 0, v81
	v_max_f32_e32 v77, 0, v77
	v_lshl_add_u64 v[82:83], v[146:147], 1, v[82:83]
	v_max_f32_e32 v78, 0, v78
	v_mul_f32_e32 v74, v74, v74
	v_mul_f32_e32 v75, v75, v75
	v_mul_f32_e32 v76, v76, v76
	v_mul_f32_e32 v77, v77, v77
	v_mul_f32_e32 v78, v78, v78
	v_cvt_pk_bf16_f32 v74, v78, v74
	v_cvt_pk_bf16_f32 v75, v75, v76
	v_cvt_pk_bf16_f32 v76, v84, v79
	v_cvt_pk_bf16_f32 v77, v80, v77
	global_store_dwordx4 v[82:83], v[74:77], off
	v_max_f32_e32 v66, 0, v66
	v_max_f32_e32 v67, 0, v67
	v_max_f32_e32 v68, 0, v68
	v_mul_f32_e32 v74, v66, v66
	v_max_f32_e32 v66, v71, v71
	v_mul_f32_e32 v71, v67, v67
	v_max_f32_e32 v67, v72, v72
	v_mul_f32_e32 v72, v68, v68
	v_max_f32_e32 v66, 0, v66
	v_max_f32_e32 v67, 0, v67
	v_max_f32_e32 v68, 0, v73
	v_max_f32_e32 v69, 0, v69
	v_max_f32_e32 v70, 0, v70
	v_mul_f32_e32 v66, v66, v66
	v_mul_f32_e32 v67, v67, v67
	v_mul_f32_e32 v68, v68, v68
	v_mul_f32_e32 v69, v69, v69
	v_mul_f32_e32 v70, v70, v70
	v_cvt_pk_bf16_f32 v66, v70, v66
	v_cvt_pk_bf16_f32 v67, v67, v68
	v_cvt_pk_bf16_f32 v68, v74, v71
	v_cvt_pk_bf16_f32 v69, v72, v69
	global_store_dwordx4 v[82:83], v[66:69], off offset:64
	s_nop 1
	v_lshlrev_b64 v[66:67], 13, v[148:149]
	v_max_f32_e32 v58, 0, v58
	v_max_f32_e32 v59, 0, v59
	v_max_f32_e32 v60, 0, v60
	v_lshl_add_u64 v[66:67], s[52:53], 0, v[66:67]
	v_mul_f32_e32 v68, v58, v58
	v_max_f32_e32 v58, v63, v63
	v_mul_f32_e32 v63, v59, v59
	v_max_f32_e32 v59, v64, v64
	v_mul_f32_e32 v64, v60, v60
	v_lshl_add_u64 v[66:67], v[146:147], 1, v[66:67]
	v_max_f32_e32 v58, 0, v58
	v_max_f32_e32 v59, 0, v59
	v_max_f32_e32 v60, 0, v65
	v_max_f32_e32 v61, 0, v61
	v_lshl_add_u64 v[66:67], v[66:67], 0, s[16:17]
	v_max_f32_e32 v62, 0, v62
	v_mul_f32_e32 v58, v58, v58
	v_mul_f32_e32 v59, v59, v59
	v_mul_f32_e32 v60, v60, v60
	v_mul_f32_e32 v61, v61, v61
	v_mul_f32_e32 v62, v62, v62
	v_cvt_pk_bf16_f32 v58, v62, v58
	v_cvt_pk_bf16_f32 v59, v59, v60
	v_cvt_pk_bf16_f32 v60, v68, v63
	v_cvt_pk_bf16_f32 v61, v64, v61
	global_store_dwordx4 v[66:67], v[58:61], off
	v_max_f32_e32 v50, 0, v50
	v_max_f32_e32 v51, 0, v51
	v_max_f32_e32 v52, 0, v52
	v_mul_f32_e32 v58, v50, v50
	v_max_f32_e32 v50, v55, v55
	v_mul_f32_e32 v55, v51, v51
	v_max_f32_e32 v51, v56, v56
	v_mul_f32_e32 v56, v52, v52
	v_max_f32_e32 v50, 0, v50
	v_max_f32_e32 v51, 0, v51
	v_max_f32_e32 v52, 0, v57
	v_max_f32_e32 v53, 0, v53
	v_max_f32_e32 v54, 0, v54
	v_mul_f32_e32 v50, v50, v50
	v_mul_f32_e32 v51, v51, v51
	v_mul_f32_e32 v52, v52, v52
	v_mul_f32_e32 v53, v53, v53
	v_mul_f32_e32 v54, v54, v54
	v_cvt_pk_bf16_f32 v50, v54, v50
	v_cvt_pk_bf16_f32 v51, v51, v52
	v_cvt_pk_bf16_f32 v52, v58, v55
	v_cvt_pk_bf16_f32 v53, v56, v53
	global_store_dwordx4 v[66:67], v[50:53], off offset:64
	s_nop 1
	v_lshlrev_b64 v[50:51], 13, v[148:149]
	v_max_f32_e32 v42, 0, v42
	v_max_f32_e32 v43, 0, v43
	v_max_f32_e32 v44, 0, v44
	v_lshl_add_u64 v[50:51], s[52:53], 0, v[50:51]
	v_mul_f32_e32 v52, v42, v42
	v_max_f32_e32 v42, v47, v47
	v_mul_f32_e32 v47, v43, v43
	v_max_f32_e32 v43, v48, v48
	v_mul_f32_e32 v48, v44, v44
	v_lshl_add_u64 v[50:51], v[146:147], 1, v[50:51]
	v_max_f32_e32 v42, 0, v42
	v_max_f32_e32 v43, 0, v43
	v_max_f32_e32 v44, 0, v49
	v_max_f32_e32 v45, 0, v45
	v_lshl_add_u64 v[50:51], v[50:51], 0, s[18:19]
	v_max_f32_e32 v46, 0, v46
	v_mul_f32_e32 v42, v42, v42
	v_mul_f32_e32 v43, v43, v43
	v_mul_f32_e32 v44, v44, v44
	v_mul_f32_e32 v45, v45, v45
	v_mul_f32_e32 v46, v46, v46
	v_cvt_pk_bf16_f32 v42, v46, v42
	v_cvt_pk_bf16_f32 v43, v43, v44
	v_cvt_pk_bf16_f32 v44, v52, v47
	v_cvt_pk_bf16_f32 v45, v48, v45
	global_store_dwordx4 v[50:51], v[42:45], off
	v_max_f32_e32 v34, 0, v34
	v_max_f32_e32 v35, 0, v35
	v_max_f32_e32 v36, 0, v36
	v_mul_f32_e32 v42, v34, v34
	v_max_f32_e32 v34, v39, v39
	v_mul_f32_e32 v39, v35, v35
; __device__ __forceinline__ unsigned cvt_pk_bf16(float lo, float hi) { unsigned r; asm volatile("v_cvt_pk_bf16_f32 %0, %1, %2" : "=v"(r) : "v"(lo), "v"(hi)); return r; }
; #define PG8_BAR __builtin_amdgcn_s_barrier()
;     __device__ __forceinline__ void operator()(const f32x4 (&acc)[2][2][4][2], const Unit& u, int wr, int wc, int fr, int fq) const {
;     ...
;         for (int ai = 0; ai < 2; ++ai)
; #pragma unroll
;             for (int m = 0; m < 4; ++m) { bf16_t* rowp = O + (size_t)(row0 + ai * HALF + m * 16) * ldc + col0;
; #pragma unroll
;                 for (int bj = 0; bj < 2; ++bj) { f32x4 v0 = acc[ai][bj][m][0], v1 = acc[ai][bj][m][1];
;                     if (ROWSCALE) { v0 = v0 * rs[ai][m]; v1 = v1 * rs[ai][m]; }
;                     if (ACT == 2) {
; #pragma unroll
;                         for (int e = 0; e < 4; ++e) { const float a = fmaxf(v0[e], 0.f), b = fmaxf(v1[e], 0.f); v0[e] = a * a; v1[e] = b * b; } }
;                     u32x4 w; w.x = cvt_pk_bf16(v0[0], v0[1]); w.y = cvt_pk_bf16(v0[2], v0[3]); w.z = cvt_pk_bf16(v1[0], v1[1]); w.w = cvt_pk_bf16(v1[2], v1[3]);
;                     if (col0 + bj * CBS < ncols) *(u32x4*)(rowp + bj * CBS) = w; } }
; template <class Epi, class Sched, bool ALIGN_EPI = false, bool SP2 = false>
; __device__ __forceinline__ void gemm_phase(PG8_LAS unsigned char* lds, const Gemm g, const Sched& S, const Epi& E) {
;     ...
;         if (!has_next) break;
; #pragma unroll
;         for (int a = 0; a < 2; ++a)
; #pragma unroll
;             for (int b = 0; b < 2; ++b)
; #pragma unroll
;                 for (int m = 0; m < 4; ++m)
; #pragma unroll
;                     for (int n = 0; n < 2; ++n) acc[a][b][m][n] = (f32x4){0.f, 0.f, 0.f, 0.f};
;         cur = nxt; cA = nA; cB = nB; ++ui;
;         if constexpr (ALIGN_EPI) { if (wr == 1) PG8_BAR; }
	v_max_f32_e32 v35, v40, v40
	v_mul_f32_e32 v40, v36, v36
	v_max_f32_e32 v34, 0, v34
	v_max_f32_e32 v35, 0, v35
	v_max_f32_e32 v36, 0, v41
	v_max_f32_e32 v37, 0, v37
	v_max_f32_e32 v38, 0, v38
	v_mul_f32_e32 v34, v34, v34
	v_mul_f32_e32 v35, v35, v35
	v_mul_f32_e32 v36, v36, v36
	v_mul_f32_e32 v37, v37, v37
	v_mul_f32_e32 v38, v38, v38
	v_cvt_pk_bf16_f32 v34, v38, v34
	v_cvt_pk_bf16_f32 v35, v35, v36
	v_cvt_pk_bf16_f32 v36, v42, v39
	v_cvt_pk_bf16_f32 v37, v40, v37
	global_store_dwordx4 v[50:51], v[34:37], off offset:64
	s_nop 1
	v_lshlrev_b64 v[34:35], 13, v[148:149]
	v_max_f32_e32 v26, 0, v26
	v_max_f32_e32 v27, 0, v27
	v_max_f32_e32 v28, 0, v28
	v_lshl_add_u64 v[34:35], s[52:53], 0, v[34:35]
	v_mul_f32_e32 v36, v26, v26
	v_max_f32_e32 v26, v31, v31
	v_mul_f32_e32 v31, v27, v27
	v_max_f32_e32 v27, v32, v32
	v_mul_f32_e32 v32, v28, v28
	v_lshl_add_u64 v[34:35], v[146:147], 1, v[34:35]
	v_max_f32_e32 v26, 0, v26
	v_max_f32_e32 v27, 0, v27
	v_max_f32_e32 v28, 0, v33
	v_max_f32_e32 v29, 0, v29
	v_lshl_add_u64 v[34:35], v[34:35], 0, s[20:21]
	v_max_f32_e32 v30, 0, v30
	v_mul_f32_e32 v26, v26, v26
	v_mul_f32_e32 v27, v27, v27
	v_mul_f32_e32 v28, v28, v28
	v_mul_f32_e32 v29, v29, v29
	v_mul_f32_e32 v30, v30, v30
	v_cvt_pk_bf16_f32 v26, v30, v26
	v_cvt_pk_bf16_f32 v27, v27, v28
	v_cvt_pk_bf16_f32 v28, v36, v31
	v_cvt_pk_bf16_f32 v29, v32, v29
	global_store_dwordx4 v[34:35], v[26:29], off
	v_max_f32_e32 v18, 0, v18
	v_max_f32_e32 v19, 0, v19
	v_max_f32_e32 v20, 0, v20
	v_mul_f32_e32 v26, v18, v18
	v_max_f32_e32 v18, v23, v23
	v_mul_f32_e32 v23, v19, v19
	v_max_f32_e32 v19, v24, v24
	v_mul_f32_e32 v24, v20, v20
	v_max_f32_e32 v18, 0, v18
	v_max_f32_e32 v19, 0, v19
	v_max_f32_e32 v20, 0, v25
	v_max_f32_e32 v21, 0, v21
	v_max_f32_e32 v22, 0, v22
	v_mul_f32_e32 v18, v18, v18
	v_mul_f32_e32 v19, v19, v19
	v_mul_f32_e32 v20, v20, v20
	v_mul_f32_e32 v21, v21, v21
	v_mul_f32_e32 v22, v22, v22
	v_cvt_pk_bf16_f32 v18, v22, v18
	v_cvt_pk_bf16_f32 v19, v19, v20
	v_cvt_pk_bf16_f32 v20, v26, v23
	v_cvt_pk_bf16_f32 v21, v24, v21
	global_store_dwordx4 v[34:35], v[18:21], off offset:64
	s_nop 1
	v_lshlrev_b64 v[18:19], 13, v[148:149]
	v_max_f32_e32 v10, 0, v10
	v_max_f32_e32 v11, 0, v11
	v_max_f32_e32 v12, 0, v12
	v_lshl_add_u64 v[18:19], s[52:53], 0, v[18:19]
	v_mul_f32_e32 v20, v10, v10
	v_max_f32_e32 v10, v15, v15
	v_mul_f32_e32 v15, v11, v11
	v_max_f32_e32 v11, v16, v16
	v_mul_f32_e32 v16, v12, v12
	v_lshl_add_u64 v[18:19], v[146:147], 1, v[18:19]
	v_max_f32_e32 v10, 0, v10
	v_max_f32_e32 v11, 0, v11
	v_max_f32_e32 v12, 0, v17
	v_max_f32_e32 v13, 0, v13
	v_lshl_add_u64 v[18:19], v[18:19], 0, s[22:23]
	v_max_f32_e32 v14, 0, v14
	v_mul_f32_e32 v10, v10, v10
	v_mul_f32_e32 v11, v11, v11
	v_mul_f32_e32 v12, v12, v12
	v_mul_f32_e32 v13, v13, v13
	v_mul_f32_e32 v14, v14, v14
	v_cvt_pk_bf16_f32 v10, v14, v10
	v_cvt_pk_bf16_f32 v11, v11, v12
	v_cvt_pk_bf16_f32 v12, v20, v15
	v_cvt_pk_bf16_f32 v13, v16, v13
	global_store_dwordx4 v[18:19], v[10:13], off
	v_max_f32_e32 v2, 0, v2
	v_max_f32_e32 v3, 0, v3
	v_max_f32_e32 v4, 0, v4
	v_mul_f32_e32 v10, v2, v2
	v_max_f32_e32 v2, v7, v7
	v_mul_f32_e32 v7, v3, v3
	v_max_f32_e32 v3, v8, v8
	v_mul_f32_e32 v8, v4, v4
	v_max_f32_e32 v2, 0, v2
	v_max_f32_e32 v3, 0, v3
	v_max_f32_e32 v4, 0, v9
	v_max_f32_e32 v5, 0, v5
	v_max_f32_e32 v6, 0, v6
	v_mul_f32_e32 v2, v2, v2
	v_mul_f32_e32 v3, v3, v3
	v_mul_f32_e32 v4, v4, v4
	v_mul_f32_e32 v5, v5, v5
	v_mul_f32_e32 v6, v6, v6
	v_cvt_pk_bf16_f32 v2, v6, v2
	v_cvt_pk_bf16_f32 v3, v3, v4
	v_cvt_pk_bf16_f32 v4, v10, v7
	v_cvt_pk_bf16_f32 v5, v8, v5
	global_store_dwordx4 v[18:19], v[2:5], off offset:64
	s_andn2_b64 vcc, exec, s[6:7]
	s_mov_b64 s[6:7], -1
	s_cbranch_vccnz .LBB0_1305
	s_andn2_b64 vcc, exec, s[0:1]
	s_cbranch_vccnz .LBB0_1304
	s_barrier
	s_branch .LBB0_1304
